# adds GEMM residual epilogue loading the residual vectors of 4 sub-blocks at once (4 waits per tile instead of 16) on top of the session best
# speedup vs baseline: 1.0040x; 1.0013x over previous
; template <class TileFn, class Epi>
; DI void gemm_stream(int ntiles, int lda, int ldb, int K, TileFn tile_fn, Epi epi) {
;     ...
;       for (int ai = 0; ai < 2; ++ai)
; #pragma unroll
;         for (int bj = 0; bj < 2; ++bj)
; #pragma unroll
;           for (int m = 0; m < 4; ++m)
;             epi(cur.sub, cur.brow + ai * HALF + wr * 64 + m * 16 + fr, cur.bcol + bj * HALF + wc * 32 + fq * 8, acc[ai][bj][m][0], acc[ai][bj][m][1]);
;   DI void operator()(int sub, int row, int col, f32x4 v, f32x4 w) const {
;     ...
;       float* X = p.xs;
;       float4* q = reinterpret_cast<float4*>(X + (size_t)row * DM + col);
;       const float4* qi = (kind == 4 && lay == 0) ? reinterpret_cast<const float4*>((const float*)p.in[I_X] + (size_t)row * DM + col) : q;
;       float4 x = qi[0], y = qi[1];
;       x.x = ALPHA * x.x + v[0]; x.y = ALPHA * x.y + v[1]; x.z = ALPHA * x.z + v[2]; x.w = ALPHA * x.w + v[3];
;       y.x = ALPHA * y.x + w[0]; y.y = ALPHA * y.y + w[1]; y.z = ALPHA * y.z + w[2]; y.w = ALPHA * y.w + w[3];
;       q[0] = x; q[1] = y;
.LBB0_401:
	global_load_dwordx4 v[138:141], v[136:137], off
	global_load_dwordx4 v[142:145], v[136:137], off offset:16
	s_mov_b64 s[2:3], 0x10000
	v_lshl_add_u64 v[176:177], v[136:137], 0, s[2:3]
	global_load_dwordx4 v[152:155], v[176:177], off
	global_load_dwordx4 v[156:159], v[176:177], off offset:16
	v_lshl_add_u64 v[176:177], v[176:177], 0, s[2:3]
	global_load_dwordx4 v[160:163], v[176:177], off
	global_load_dwordx4 v[164:167], v[176:177], off offset:16
	v_lshl_add_u64 v[176:177], v[176:177], 0, s[2:3]
	global_load_dwordx4 v[168:171], v[176:177], off
	global_load_dwordx4 v[172:175], v[176:177], off offset:16
	s_waitcnt vmcnt(0)
	v_pk_fma_f32 v[136:137], v[138:139], s[56:57], v[126:127] op_sel_hi:[1,0,1]
	v_pk_fma_f32 v[138:139], v[140:141], s[56:57], v[128:129] op_sel_hi:[1,0,1]
	v_pk_fma_f32 v[140:141], v[142:143], s[56:57], v[122:123] op_sel_hi:[1,0,1]
	v_pk_fma_f32 v[142:143], v[144:145], s[56:57], v[124:125] op_sel_hi:[1,0,1]
	global_store_dwordx4 v[134:135], v[136:139], off
	global_store_dwordx4 v[134:135], v[140:143], off offset:16

;   DI void operator()(int sub, int row, int col, f32x4 v, f32x4 w) const {
;     ...
;       float4 x = qi[0], y = qi[1];
;       x.x = ALPHA * x.x + v[0]; x.y = ALPHA * x.y + v[1]; x.z = ALPHA * x.z + v[2]; x.w = ALPHA * x.w + v[3];
;       y.x = ALPHA * y.x + w[0]; y.y = ALPHA * y.y + w[1]; y.z = ALPHA * y.z + w[2]; y.w = ALPHA * y.w + w[3];
;       q[0] = x; q[1] = y;
.LBB0_448:
	v_pk_fma_f32 v[140:141], v[152:153], s[56:57], v[110:111] op_sel_hi:[1,0,1]
	v_pk_fma_f32 v[142:143], v[154:155], s[56:57], v[112:113] op_sel_hi:[1,0,1]
	v_pk_fma_f32 v[144:145], v[156:157], s[56:57], v[106:107] op_sel_hi:[1,0,1]
	v_pk_fma_f32 v[146:147], v[158:159], s[56:57], v[108:109] op_sel_hi:[1,0,1]
	global_store_dwordx4 v[134:135], v[140:143], off
	global_store_dwordx4 v[134:135], v[144:147], off offset:16
	s_cmp_lt_i32 s67, 8
	s_cbranch_scc0 .LBB0_413

;   DI void operator()(int sub, int row, int col, f32x4 v, f32x4 w) const {
;     ...
;       float4 x = qi[0], y = qi[1];
;       x.x = ALPHA * x.x + v[0]; x.y = ALPHA * x.y + v[1]; x.z = ALPHA * x.z + v[2]; x.w = ALPHA * x.w + v[3];
;       y.x = ALPHA * y.x + w[0]; y.y = ALPHA * y.y + w[1]; y.z = ALPHA * y.z + w[2]; y.w = ALPHA * y.w + w[3];
;       q[0] = x; q[1] = y;
.LBB0_489:
	v_pk_fma_f32 v[140:141], v[160:161], s[56:57], v[94:95] op_sel_hi:[1,0,1]
	v_pk_fma_f32 v[142:143], v[162:163], s[56:57], v[96:97] op_sel_hi:[1,0,1]
	v_pk_fma_f32 v[144:145], v[164:165], s[56:57], v[90:91] op_sel_hi:[1,0,1]
	v_pk_fma_f32 v[146:147], v[166:167], s[56:57], v[92:93] op_sel_hi:[1,0,1]
	global_store_dwordx4 v[134:135], v[140:143], off
	global_store_dwordx4 v[134:135], v[144:147], off offset:16
	s_cmp_lt_i32 s67, 8
	s_cbranch_scc0 .LBB0_454

;   DI void operator()(int sub, int row, int col, f32x4 v, f32x4 w) const {
;     ...
;       float4 x = qi[0], y = qi[1];
;       x.x = ALPHA * x.x + v[0]; x.y = ALPHA * x.y + v[1]; x.z = ALPHA * x.z + v[2]; x.w = ALPHA * x.w + v[3];
;       y.x = ALPHA * y.x + w[0]; y.y = ALPHA * y.y + w[1]; y.z = ALPHA * y.z + w[2]; y.w = ALPHA * y.w + w[3];
;       q[0] = x; q[1] = y;
.LBB0_524:
	v_pk_fma_f32 v[142:143], v[168:169], s[56:57], v[78:79] op_sel_hi:[1,0,1]
	v_pk_fma_f32 v[144:145], v[170:171], s[56:57], v[80:81] op_sel_hi:[1,0,1]
	v_pk_fma_f32 v[146:147], v[172:173], s[56:57], v[74:75] op_sel_hi:[1,0,1]
	v_pk_fma_f32 v[148:149], v[174:175], s[56:57], v[76:77] op_sel_hi:[1,0,1]
	global_store_dwordx4 v[140:141], v[142:145], off
	global_store_dwordx4 v[140:141], v[146:149], off offset:16

;   DI void operator()(int sub, int row, int col, f32x4 v, f32x4 w) const {
;     ...
;       float* X = p.xs;
;       float4* q = reinterpret_cast<float4*>(X + (size_t)row * DM + col);
;       const float4* qi = (kind == 4 && lay == 0) ? reinterpret_cast<const float4*>((const float*)p.in[I_X] + (size_t)row * DM + col) : q;
;       float4 x = qi[0], y = qi[1];
;       x.x = ALPHA * x.x + v[0]; x.y = ALPHA * x.y + v[1]; x.z = ALPHA * x.z + v[2]; x.w = ALPHA * x.w + v[3];
;       y.x = ALPHA * y.x + w[0]; y.y = ALPHA * y.y + w[1]; y.z = ALPHA * y.z + w[2]; y.w = ALPHA * y.w + w[3];
;       q[0] = x; q[1] = y;
.LBB0_572:
	global_load_dwordx4 v[144:147], v[142:143], off
	global_load_dwordx4 v[148:151], v[142:143], off offset:16
	s_mov_b64 s[2:3], 0x10000
	v_lshl_add_u64 v[176:177], v[142:143], 0, s[2:3]
	global_load_dwordx4 v[152:155], v[176:177], off
	global_load_dwordx4 v[156:159], v[176:177], off offset:16
	v_lshl_add_u64 v[176:177], v[176:177], 0, s[2:3]
	global_load_dwordx4 v[160:163], v[176:177], off
	global_load_dwordx4 v[164:167], v[176:177], off offset:16
	v_lshl_add_u64 v[176:177], v[176:177], 0, s[2:3]
	global_load_dwordx4 v[168:171], v[176:177], off
	global_load_dwordx4 v[172:175], v[176:177], off offset:16
	s_waitcnt vmcnt(0)
	v_pk_fma_f32 v[142:143], v[144:145], s[56:57], v[118:119] op_sel_hi:[1,0,1]
	v_pk_fma_f32 v[144:145], v[146:147], s[56:57], v[120:121] op_sel_hi:[1,0,1]
	v_pk_fma_f32 v[146:147], v[148:149], s[56:57], v[114:115] op_sel_hi:[1,0,1]
	v_pk_fma_f32 v[148:149], v[150:151], s[56:57], v[116:117] op_sel_hi:[1,0,1]
	global_store_dwordx4 v[140:141], v[142:145], off offset:512
	global_store_dwordx4 v[140:141], v[146:149], off offset:528
	s_cmp_lt_i32 s67, 8
	s_cbranch_scc0 .LBB0_536

;   DI void operator()(int sub, int row, int col, f32x4 v, f32x4 w) const {
;     ...
;       float4 x = qi[0], y = qi[1];
;       x.x = ALPHA * x.x + v[0]; x.y = ALPHA * x.y + v[1]; x.z = ALPHA * x.z + v[2]; x.w = ALPHA * x.w + v[3];
;       y.x = ALPHA * y.x + w[0]; y.y = ALPHA * y.y + w[1]; y.z = ALPHA * y.z + w[2]; y.w = ALPHA * y.w + w[3];
;       q[0] = x; q[1] = y;
.LBB0_614:
	v_pk_fma_f32 v[142:143], v[152:153], s[56:57], v[102:103] op_sel_hi:[1,0,1]
	v_pk_fma_f32 v[144:145], v[154:155], s[56:57], v[104:105] op_sel_hi:[1,0,1]
	v_pk_fma_f32 v[146:147], v[156:157], s[56:57], v[98:99] op_sel_hi:[1,0,1]
	v_pk_fma_f32 v[148:149], v[158:159], s[56:57], v[100:101] op_sel_hi:[1,0,1]
	global_store_dwordx4 v[140:141], v[142:145], off offset:512
	global_store_dwordx4 v[140:141], v[146:149], off offset:528
	s_cmp_lt_i32 s67, 8
	s_cbranch_scc0 .LBB0_578

;   DI void operator()(int sub, int row, int col, f32x4 v, f32x4 w) const {
;     ...
;       float4 x = qi[0], y = qi[1];
;       x.x = ALPHA * x.x + v[0]; x.y = ALPHA * x.y + v[1]; x.z = ALPHA * x.z + v[2]; x.w = ALPHA * x.w + v[3];
;       y.x = ALPHA * y.x + w[0]; y.y = ALPHA * y.y + w[1]; y.z = ALPHA * y.z + w[2]; y.w = ALPHA * y.w + w[3];
;       q[0] = x; q[1] = y;
.LBB0_656:
	v_pk_fma_f32 v[140:141], v[160:161], s[56:57], v[86:87] op_sel_hi:[1,0,1]
	v_pk_fma_f32 v[142:143], v[162:163], s[56:57], v[88:89] op_sel_hi:[1,0,1]
	v_pk_fma_f32 v[144:145], v[164:165], s[56:57], v[82:83] op_sel_hi:[1,0,1]
	v_pk_fma_f32 v[146:147], v[166:167], s[56:57], v[84:85] op_sel_hi:[1,0,1]
	global_store_dwordx4 v[138:139], v[140:143], off offset:512
	global_store_dwordx4 v[138:139], v[144:147], off offset:528
	s_cmp_lt_i32 s67, 8
	s_cbranch_scc0 .LBB0_620

;   DI void operator()(int sub, int row, int col, f32x4 v, f32x4 w) const {
;     ...
;       float4 x = qi[0], y = qi[1];
;       x.x = ALPHA * x.x + v[0]; x.y = ALPHA * x.y + v[1]; x.z = ALPHA * x.z + v[2]; x.w = ALPHA * x.w + v[3];
;       y.x = ALPHA * y.x + w[0]; y.y = ALPHA * y.y + w[1]; y.z = ALPHA * y.z + w[2]; y.w = ALPHA * y.w + w[3];
;       q[0] = x; q[1] = y;
.LBB0_698:
	v_pk_fma_f32 v[138:139], v[168:169], s[56:57], v[70:71] op_sel_hi:[1,0,1]
	v_pk_fma_f32 v[140:141], v[170:171], s[56:57], v[72:73] op_sel_hi:[1,0,1]
	v_pk_fma_f32 v[142:143], v[172:173], s[56:57], v[66:67] op_sel_hi:[1,0,1]
	v_pk_fma_f32 v[144:145], v[174:175], s[56:57], v[68:69] op_sel_hi:[1,0,1]
	global_store_dwordx4 v[136:137], v[138:141], off offset:512
	global_store_dwordx4 v[136:137], v[142:145], off offset:528
	s_cmp_lt_i32 s67, 8
	s_cbranch_scc0 .LBB0_662

;   DI void operator()(int sub, int row, int col, f32x4 v, f32x4 w) const {
;     ...
;       float* X = p.xs;
;       float4* q = reinterpret_cast<float4*>(X + (size_t)row * DM + col);
;       const float4* qi = (kind == 4 && lay == 0) ? reinterpret_cast<const float4*>((const float*)p.in[I_X] + (size_t)row * DM + col) : q;
;       float4 x = qi[0], y = qi[1];
;       x.x = ALPHA * x.x + v[0]; x.y = ALPHA * x.y + v[1]; x.z = ALPHA * x.z + v[2]; x.w = ALPHA * x.w + v[3];
;       y.x = ALPHA * y.x + w[0]; y.y = ALPHA * y.y + w[1]; y.z = ALPHA * y.z + w[2]; y.w = ALPHA * y.w + w[3];
;       q[0] = x; q[1] = y;
.LBB0_739:
	global_load_dwordx4 v[140:143], v[136:137], off
	global_load_dwordx4 v[144:147], v[136:137], off offset:16
	s_mov_b64 s[2:3], 0x10000
	v_lshl_add_u64 v[176:177], v[136:137], 0, s[2:3]
	global_load_dwordx4 v[152:155], v[176:177], off
	global_load_dwordx4 v[156:159], v[176:177], off offset:16
	v_lshl_add_u64 v[176:177], v[176:177], 0, s[2:3]
	global_load_dwordx4 v[160:163], v[176:177], off
	global_load_dwordx4 v[164:167], v[176:177], off offset:16
	v_lshl_add_u64 v[176:177], v[176:177], 0, s[2:3]
	global_load_dwordx4 v[168:171], v[176:177], off
	global_load_dwordx4 v[172:175], v[176:177], off offset:16
	s_waitcnt vmcnt(0)
	v_pk_fma_f32 v[140:141], v[140:141], s[56:57], v[62:63] op_sel_hi:[1,0,1]
	v_pk_fma_f32 v[142:143], v[142:143], s[56:57], v[64:65] op_sel_hi:[1,0,1]
	v_pk_fma_f32 v[144:145], v[144:145], s[56:57], v[58:59] op_sel_hi:[1,0,1]
	v_pk_fma_f32 v[146:147], v[146:147], s[56:57], v[60:61] op_sel_hi:[1,0,1]
	global_store_dwordx4 v[134:135], v[140:143], off
	global_store_dwordx4 v[134:135], v[144:147], off offset:16
	s_cmp_lt_i32 s67, 8
	s_cbranch_scc0 .LBB0_704

;   DI void operator()(int sub, int row, int col, f32x4 v, f32x4 w) const {
;     ...
;       float4 x = qi[0], y = qi[1];
;       x.x = ALPHA * x.x + v[0]; x.y = ALPHA * x.y + v[1]; x.z = ALPHA * x.z + v[2]; x.w = ALPHA * x.w + v[3];
;       y.x = ALPHA * y.x + w[0]; y.y = ALPHA * y.y + w[1]; y.z = ALPHA * y.z + w[2]; y.w = ALPHA * y.w + w[3];
;       q[0] = x; q[1] = y;
.LBB0_780:
	v_pk_fma_f32 v[140:141], v[152:153], s[56:57], v[46:47] op_sel_hi:[1,0,1]
	v_pk_fma_f32 v[142:143], v[154:155], s[56:57], v[48:49] op_sel_hi:[1,0,1]
	v_pk_fma_f32 v[144:145], v[156:157], s[56:57], v[42:43] op_sel_hi:[1,0,1]
	v_pk_fma_f32 v[146:147], v[158:159], s[56:57], v[44:45] op_sel_hi:[1,0,1]
	global_store_dwordx4 v[134:135], v[140:143], off
	global_store_dwordx4 v[134:135], v[144:147], off offset:16
	s_cmp_lt_i32 s67, 8
	s_cbranch_scc0 .LBB0_745

;   DI void operator()(int sub, int row, int col, f32x4 v, f32x4 w) const {
;     ...
;       float4 x = qi[0], y = qi[1];
;       x.x = ALPHA * x.x + v[0]; x.y = ALPHA * x.y + v[1]; x.z = ALPHA * x.z + v[2]; x.w = ALPHA * x.w + v[3];
;       y.x = ALPHA * y.x + w[0]; y.y = ALPHA * y.y + w[1]; y.z = ALPHA * y.z + w[2]; y.w = ALPHA * y.w + w[3];
;       q[0] = x; q[1] = y;
.LBB0_821:
	v_pk_fma_f32 v[142:143], v[160:161], s[56:57], v[30:31] op_sel_hi:[1,0,1]
	v_pk_fma_f32 v[144:145], v[162:163], s[56:57], v[32:33] op_sel_hi:[1,0,1]
	v_pk_fma_f32 v[146:147], v[164:165], s[56:57], v[26:27] op_sel_hi:[1,0,1]
	v_pk_fma_f32 v[148:149], v[166:167], s[56:57], v[28:29] op_sel_hi:[1,0,1]
	global_store_dwordx4 v[140:141], v[142:145], off
	global_store_dwordx4 v[140:141], v[146:149], off offset:16
	s_cmp_lt_i32 s67, 8
	s_cbranch_scc0 .LBB0_786

;   DI void operator()(int sub, int row, int col, f32x4 v, f32x4 w) const {
;     ...
;       float4 x = qi[0], y = qi[1];
;       x.x = ALPHA * x.x + v[0]; x.y = ALPHA * x.y + v[1]; x.z = ALPHA * x.z + v[2]; x.w = ALPHA * x.w + v[3];
;       y.x = ALPHA * y.x + w[0]; y.y = ALPHA * y.y + w[1]; y.z = ALPHA * y.z + w[2]; y.w = ALPHA * y.w + w[3];
;       q[0] = x; q[1] = y;
.LBB0_856:
	v_pk_fma_f32 v[142:143], v[168:169], s[56:57], v[12:13] op_sel_hi:[1,0,1]
	v_pk_fma_f32 v[144:145], v[170:171], s[56:57], v[14:15] op_sel_hi:[1,0,1]
	v_pk_fma_f32 v[146:147], v[172:173], s[56:57], v[8:9] op_sel_hi:[1,0,1]
	v_pk_fma_f32 v[148:149], v[174:175], s[56:57], v[10:11] op_sel_hi:[1,0,1]
	global_store_dwordx4 v[140:141], v[142:145], off
	global_store_dwordx4 v[140:141], v[146:149], off offset:16

;   DI void operator()(int sub, int row, int col, f32x4 v, f32x4 w) const {
;     ...
;       float* X = p.xs;
;       float4* q = reinterpret_cast<float4*>(X + (size_t)row * DM + col);
;       const float4* qi = (kind == 4 && lay == 0) ? reinterpret_cast<const float4*>((const float*)p.in[I_X] + (size_t)row * DM + col) : q;
;       float4 x = qi[0], y = qi[1];
;       x.x = ALPHA * x.x + v[0]; x.y = ALPHA * x.y + v[1]; x.z = ALPHA * x.z + v[2]; x.w = ALPHA * x.w + v[3];
;       y.x = ALPHA * y.x + w[0]; y.y = ALPHA * y.y + w[1]; y.z = ALPHA * y.z + w[2]; y.w = ALPHA * y.w + w[3];
;       q[0] = x; q[1] = y;
.LBB0_904:
	global_load_dwordx4 v[140:143], v[138:139], off
	global_load_dwordx4 v[144:147], v[138:139], off offset:16
	s_mov_b64 s[2:3], 0x10000
	v_lshl_add_u64 v[176:177], v[138:139], 0, s[2:3]
	global_load_dwordx4 v[152:155], v[176:177], off
	global_load_dwordx4 v[156:159], v[176:177], off offset:16
	v_lshl_add_u64 v[176:177], v[176:177], 0, s[2:3]
	global_load_dwordx4 v[160:163], v[176:177], off
	global_load_dwordx4 v[164:167], v[176:177], off offset:16
	v_lshl_add_u64 v[176:177], v[176:177], 0, s[2:3]
	global_load_dwordx4 v[168:171], v[176:177], off
	global_load_dwordx4 v[172:175], v[176:177], off offset:16
	s_waitcnt vmcnt(0)
	v_pk_fma_f32 v[138:139], v[140:141], s[56:57], v[54:55] op_sel_hi:[1,0,1]
	v_pk_fma_f32 v[140:141], v[142:143], s[56:57], v[56:57] op_sel_hi:[1,0,1]
	v_pk_fma_f32 v[142:143], v[144:145], s[56:57], v[50:51] op_sel_hi:[1,0,1]
	v_pk_fma_f32 v[144:145], v[146:147], s[56:57], v[52:53] op_sel_hi:[1,0,1]
	global_store_dwordx4 v[130:131], v[138:141], off offset:512
	global_store_dwordx4 v[130:131], v[142:145], off offset:528
	s_cmp_lt_i32 s67, 8
	s_cbranch_scc0 .LBB0_868

;   DI void operator()(int sub, int row, int col, f32x4 v, f32x4 w) const {
;     ...
;       float4 x = qi[0], y = qi[1];
;       x.x = ALPHA * x.x + v[0]; x.y = ALPHA * x.y + v[1]; x.z = ALPHA * x.z + v[2]; x.w = ALPHA * x.w + v[3];
;       y.x = ALPHA * y.x + w[0]; y.y = ALPHA * y.y + w[1]; y.z = ALPHA * y.z + w[2]; y.w = ALPHA * y.w + w[3];
;       q[0] = x; q[1] = y;
.LBB0_946:
	v_pk_fma_f32 v[136:137], v[152:153], s[56:57], v[38:39] op_sel_hi:[1,0,1]
	v_pk_fma_f32 v[138:139], v[154:155], s[56:57], v[40:41] op_sel_hi:[1,0,1]
	v_pk_fma_f32 v[140:141], v[156:157], s[56:57], v[34:35] op_sel_hi:[1,0,1]
	v_pk_fma_f32 v[142:143], v[158:159], s[56:57], v[36:37] op_sel_hi:[1,0,1]
	global_store_dwordx4 v[130:131], v[136:139], off offset:512
	global_store_dwordx4 v[130:131], v[140:143], off offset:528
	s_cmp_lt_i32 s67, 8
	s_cbranch_scc0 .LBB0_910

;   DI void operator()(int sub, int row, int col, f32x4 v, f32x4 w) const {
;     ...
;       float4 x = qi[0], y = qi[1];
;       x.x = ALPHA * x.x + v[0]; x.y = ALPHA * x.y + v[1]; x.z = ALPHA * x.z + v[2]; x.w = ALPHA * x.w + v[3];
;       y.x = ALPHA * y.x + w[0]; y.y = ALPHA * y.y + w[1]; y.z = ALPHA * y.z + w[2]; y.w = ALPHA * y.w + w[3];
;       q[0] = x; q[1] = y;
.LBB0_988:
	v_pk_fma_f32 v[134:135], v[160:161], s[56:57], v[22:23] op_sel_hi:[1,0,1]
	v_pk_fma_f32 v[136:137], v[162:163], s[56:57], v[24:25] op_sel_hi:[1,0,1]
	v_pk_fma_f32 v[138:139], v[164:165], s[56:57], v[18:19] op_sel_hi:[1,0,1]
	v_pk_fma_f32 v[140:141], v[166:167], s[56:57], v[20:21] op_sel_hi:[1,0,1]
	global_store_dwordx4 v[130:131], v[134:137], off offset:512
	global_store_dwordx4 v[130:131], v[138:141], off offset:528
	s_cmp_lt_i32 s67, 8
	s_cbranch_scc0 .LBB0_952

;   DI void operator()(int sub, int row, int col, f32x4 v, f32x4 w) const {
;     ...
;       float4 x = qi[0], y = qi[1];
;       x.x = ALPHA * x.x + v[0]; x.y = ALPHA * x.y + v[1]; x.z = ALPHA * x.z + v[2]; x.w = ALPHA * x.w + v[3];
;       y.x = ALPHA * y.x + w[0]; y.y = ALPHA * y.y + w[1]; y.z = ALPHA * y.z + w[2]; y.w = ALPHA * y.w + w[3];
;       q[0] = x; q[1] = y;
.LBB0_1024:
	v_pk_fma_f32 v[132:133], v[168:169], s[56:57], v[4:5] op_sel_hi:[1,0,1]
	v_pk_fma_f32 v[134:135], v[170:171], s[56:57], v[6:7] op_sel_hi:[1,0,1]
	v_pk_fma_f32 v[136:137], v[172:173], s[56:57], v[0:1] op_sel_hi:[1,0,1]
	v_pk_fma_f32 v[138:139], v[174:175], s[56:57], v[2:3] op_sel_hi:[1,0,1]
	global_store_dwordx4 v[130:131], v[132:135], off offset:512
	global_store_dwordx4 v[130:131], v[136:139], off offset:528
